# barrier census loads batched; a3/a1 loop-top counted waits (no store-ack wait); a3 next-item lb loads issued before tail stores
# speedup vs baseline: 1.0121x; 1.0121x over previous
; __device__ __forceinline__ unsigned xb_ld(unsigned* p)              { return __hip_atomic_load(p, __ATOMIC_RELAXED, __HIP_MEMORY_SCOPE_AGENT); }
; __device__ __forceinline__ void xcd_barrier_complete(unsigned* bar, unsigned x, unsigned& nloc, unsigned& nx) {
;     const unsigned G = gridDim.x * gridDim.y * gridDim.z;
;     unsigned sum, cnt, mine, sp = 0u;
;     for (;;) {
;         sum = 0u; cnt = 0u; mine = 0u;
; #pragma unroll
;         for (unsigned j = 0; j < 16; ++j) { const unsigned c = xb_ld(&bar[XB_XCNT(j)]); sum += c; cnt += (c > 0u) ? 1u : 0u; mine = (j == x) ? c : mine; }
;         if (sum == G) break;
;         __builtin_amdgcn_s_sleep(1);
;         if ((++sp & 255u) == 0u) { if (xb_ld(&bar[XB_TMO])) break; if (sp > XB_SPIN_CAP) { atomicAdd(&bar[XB_TMO], 1u); break; } }
;     }
;     nloc = mine > 0u ? mine : 1u; nx = cnt > 0u ? cnt : 1u;
; }
.LBB0_26:
	v_readlane_b32 s4, v249, 6
	v_readlane_b32 s5, v249, 7
	s_mov_b64 s[6:7], -1
	s_waitcnt lgkmcnt(0)
	s_nop 2
	global_load_dword v0, v137, s[4:5] sc1
	v_readlane_b32 s4, v249, 8
	v_readlane_b32 s5, v249, 9
	s_nop 4
	global_load_dword v1, v137, s[4:5] sc1
	v_readlane_b32 s4, v249, 10
	v_readlane_b32 s5, v249, 11
	s_nop 4
	global_load_dword v2, v137, s[4:5] sc1
	v_readlane_b32 s4, v249, 12
	v_readlane_b32 s5, v249, 13
	s_nop 4
	global_load_dword v3, v137, s[4:5] sc1
	v_readlane_b32 s4, v249, 14
	v_readlane_b32 s5, v249, 15
	s_nop 4
	global_load_dword v4, v137, s[4:5] sc1
	v_readlane_b32 s4, v249, 16
	v_readlane_b32 s5, v249, 17
	s_nop 4
	global_load_dword v5, v137, s[4:5] sc1
	v_readlane_b32 s4, v249, 18
	v_readlane_b32 s5, v249, 19
	s_nop 4
	global_load_dword v6, v137, s[4:5] sc1
	v_readlane_b32 s4, v249, 20
	v_readlane_b32 s5, v249, 21
	s_nop 4
	global_load_dword v7, v137, s[4:5] sc1
	v_readlane_b32 s4, v249, 22
	v_readlane_b32 s5, v249, 23
	s_nop 4
	global_load_dword v8, v137, s[4:5] sc1
	v_readlane_b32 s4, v249, 24
	v_readlane_b32 s5, v249, 25
	s_nop 4
	global_load_dword v9, v137, s[4:5] sc1
	v_readlane_b32 s4, v249, 26
	v_readlane_b32 s5, v249, 27
	s_nop 4
	global_load_dword v10, v137, s[4:5] sc1
	v_readlane_b32 s4, v249, 28
	v_readlane_b32 s5, v249, 29
	s_nop 4
	global_load_dword v11, v137, s[4:5] sc1
	v_readlane_b32 s4, v249, 30
	v_readlane_b32 s5, v249, 31
	s_nop 4
	global_load_dword v12, v137, s[4:5] sc1
	v_readlane_b32 s4, v249, 32
	v_readlane_b32 s5, v249, 33
	s_nop 4
	global_load_dword v13, v137, s[4:5] sc1
	v_readlane_b32 s4, v249, 34
	v_readlane_b32 s5, v249, 35
	s_nop 4
	global_load_dword v14, v137, s[4:5] sc1
	v_readlane_b32 s4, v249, 36
	v_readlane_b32 s5, v249, 37
	s_nop 4
	global_load_dword v15, v137, s[4:5] sc1
	s_mov_b64 s[4:5], -1
	s_waitcnt vmcnt(0)
	v_add_u32_e32 v16, v1, v0
	v_add_u32_e32 v16, v16, v2
	v_add_u32_e32 v16, v16, v3
	v_add_u32_e32 v16, v16, v4
	v_add_u32_e32 v16, v16, v5
	v_add_u32_e32 v16, v16, v6
	v_add_u32_e32 v16, v16, v7
	v_add_u32_e32 v16, v16, v8
	v_add_u32_e32 v16, v16, v9
	v_add_u32_e32 v16, v16, v10
	v_add_u32_e32 v16, v16, v11
	v_add_u32_e32 v16, v16, v12
	v_add_u32_e32 v16, v16, v13
	v_add_u32_e32 v16, v16, v14
	v_add_u32_e32 v16, v16, v15
	v_cmp_eq_u32_e32 vcc, s19, v16
	s_cbranch_vccnz .LBB0_25
	s_and_b32 s4, s10, 0xff
	s_cmp_eq_u32 s4, 0
	s_mov_b64 s[4:5], -1
	s_mov_b64 s[8:9], -1
	s_sleep 1
	s_cbranch_scc1 .LBB0_30
	s_and_b64 vcc, exec, s[8:9]
	s_cbranch_vccz .LBB0_25

; #define LAS __attribute__((address_space(3)))
; __device__ __forceinline__ unsigned row_addr(int lane, int s) { return off_b((unsigned)(lane & 15), (unsigned)(4 * s + (lane >> 4))); }
; template <int DK, bool ISC> ...
;     ...
;     const int tb = w & 3, vh = w >> 2, g = lane >> 4, c15 = lane & 15, t = 16 * tb + c15;
;     unsigned ra[KS];
; #pragma unroll
;     for (int kk = 0; kk < KS; ++kk) ra[kk] = row_addr(lane, kk);
; __device__ __forceinline__ void a3_load(A3Regs& R, const Params& P, int item, int tid) {
;     const int cidx = item / 6, h = item % 6; const bf16_t* proj = (const bf16_t*)(P.ws + WS_PROJ);
; #pragma unroll
;     for (int u = 0; u < 2; ++u) { const int i = tid + 512 * u; const size_t o = (size_t)(cidx * 64 + (i >> 4)) * 128 + (i & 15) * 8;
;         R.z[u] = *(const u32x4*)(pjp(proj, AF, 128, h, 0) + o); R.q[u] = *(const u32x4*)(pjp(proj, AQ, 128, h, 0) + o); R.v[u] = *(const u32x4*)(pjp(proj, AI, 128, h, 0) + o); R.g[u] = *(const u32x4*)(pjp(proj, AG, 128, h, 0) + o); }
;     const bf16_t* st = (const bf16_t*)(P.ws + WS_STA) + (size_t)(cidx * 6 + h) * 16384;
; #pragma unroll
;     for (int u = 0; u < 4; ++u) R.st[u] = *(const u32x4*)(st + (size_t)(tid + 512 * u) * 8);
; }
; __device__ __forceinline__ void a3_phase(const Params& P, int layer, LAS unsigned char* lds, int tid) {
;     const int w = tid >> 6, lane = tid & 63, kp = tid & 63, G = gridDim.x;
;     LAS float* part = (LAS float*)(lds + R_AUX);
;     A3Regs R; int it = blockIdx.x; if (it < 3072) a3_load(R, P, it, tid);
.LBB0_103:
	s_andn2_b64 vcc, exec, s[0:1]
	v_ashrrev_i32_e32 v151, 31, v150
	v_and_b32_e32 v103, 0xffffff00, v150
	s_cbranch_vccnz .LBB0_119
	v_readlane_b32 s52, v247, 14
	s_lshl_b64 s[0:1], s[36:37], 2
	v_readlane_b32 s60, v247, 22
	v_readlane_b32 s61, v247, 23
	s_add_u32 s10, s60, s0
	s_addc_u32 s11, s61, s1
	s_add_u32 s12, s4, 0xcc00000
	s_addc_u32 s13, s5, 0
	s_add_u32 s8, s4, 0xfc00000
	s_addc_u32 s9, s5, 0
	s_lshl_b64 s[0:1], s[90:91], 1
	v_readlane_b32 s53, v247, 15
	v_readlane_b32 s54, v247, 16
	v_readlane_b32 s55, v247, 17
	v_readlane_b32 s56, v247, 18
	v_readlane_b32 s57, v247, 19
	v_readlane_b32 s58, v247, 20
	v_readlane_b32 s59, v247, 21
	v_readlane_b32 s62, v247, 24
	v_readlane_b32 s63, v247, 25
	v_readlane_b32 s64, v247, 26
	v_readlane_b32 s65, v247, 27
	v_readlane_b32 s66, v247, 28
	v_readlane_b32 s67, v247, 29
	v_writelane_b32 v247, s8, 53
	s_add_u32 s8, s8, s0
	v_writelane_b32 v247, s9, 54
	s_addc_u32 s9, s9, s1
	v_writelane_b32 v247, s12, 55
	s_add_u32 s12, s12, s0
	v_writelane_b32 v247, s13, 56
	s_addc_u32 s13, s13, s1
	s_add_u32 s14, s4, 0x12c00000
	s_addc_u32 s15, s5, 0
	v_writelane_b32 v247, s14, 57
	s_add_u32 s14, s14, s0
	v_add_u32_e32 v60, 0x200, v150
	v_writelane_b32 v247, s15, 58
	s_addc_u32 s15, s15, s1
	v_ashrrev_i32_e32 v102, 4, v150
	v_ashrrev_i32_e32 v104, 4, v60
	v_lshlrev_b32_e32 v66, 3, v150
	s_add_u32 s18, s4, 0x15c00000
	s_waitcnt vmcnt(0)
	v_add_u32_e32 v0, s88, v102
	v_add_u32_e32 v16, s88, v104
	v_and_b32_e32 v48, 0x78, v66
	s_addc_u32 s19, s5, 0
	v_ashrrev_i32_e32 v1, 31, v0
	v_ashrrev_i32_e32 v17, 31, v16
	s_add_u32 s0, s18, s0
	v_lshlrev_b64 v[8:9], 8, v[0:1]
	v_lshlrev_b32_e32 v18, 1, v48
	v_lshlrev_b64 v[24:25], 8, v[16:17]
	s_addc_u32 s1, s19, s1
	v_or_b32_e32 v8, v8, v18
	v_or_b32_e32 v24, v24, v18
	v_lshl_add_u64 v[12:13], s[0:1], 0, v[8:9]
	v_lshl_add_u64 v[28:29], s[0:1], 0, v[24:25]
	v_readlane_b32 s0, v248, 18
	v_readlane_b32 s1, v248, 19
	s_add_u32 s0, s4, s0
	s_addc_u32 s1, s5, s1
	v_add_u32_e32 v62, 0x400, v150
	v_add_u32_e32 v64, 0x600, v150
	s_add_u32 s0, s0, 0x2ac00000
	v_ashrrev_i32_e32 v61, 31, v60
	v_ashrrev_i32_e32 v63, 31, v62
	v_ashrrev_i32_e32 v65, 31, v64
	s_addc_u32 s1, s1, 0
	v_lshlrev_b64 v[52:53], 4, v[150:151]
	v_lshlrev_b64 v[50:51], 4, v[60:61]
	v_lshlrev_b64 v[54:55], 4, v[62:63]
	v_lshlrev_b64 v[56:57], 4, v[64:65]
	v_lshl_add_u64 v[0:1], s[8:9], 0, v[8:9]
	v_lshl_add_u64 v[4:5], s[12:13], 0, v[8:9]
	v_lshl_add_u64 v[10:11], s[14:15], 0, v[8:9]
	v_lshl_add_u64 v[16:17], s[8:9], 0, v[24:25]
	v_lshl_add_u64 v[20:21], s[12:13], 0, v[24:25]
	v_lshl_add_u64 v[26:27], s[14:15], 0, v[24:25]
	v_lshl_add_u64 v[32:33], s[0:1], 0, v[52:53]
	v_lshl_add_u64 v[36:37], s[0:1], 0, v[50:51]
	v_lshl_add_u64 v[40:41], s[0:1], 0, v[54:55]
	v_lshl_add_u64 v[44:45], s[0:1], 0, v[56:57]
	global_load_dwordx4 v[0:3], v[0:1], off
	s_nop 0
	global_load_dwordx4 v[4:7], v[4:5], off
	s_nop 0
	global_load_dwordx4 v[8:11], v[10:11], off
	s_nop 0
	global_load_dwordx4 v[12:15], v[12:13], off
	s_nop 0
	global_load_dwordx4 v[16:19], v[16:17], off
	s_nop 0
	global_load_dwordx4 v[20:23], v[20:21], off
	s_nop 0
	global_load_dwordx4 v[24:27], v[26:27], off
	s_nop 0
	global_load_dwordx4 v[28:31], v[28:29], off
	s_nop 0
	global_load_dwordx4 v[32:35], v[32:33], off
	s_nop 0
	global_load_dwordx4 v[36:39], v[36:37], off
	s_nop 0
	global_load_dwordx4 v[40:43], v[40:41], off
	s_nop 0
	global_load_dwordx4 v[44:47], v[44:45], off
	v_and_b32_e32 v58, 63, v150
	v_lshlrev_b32_e32 v65, 2, v58
	v_and_b32_e32 v61, 15, v150
	v_add_u32_e32 v67, 0, v65
	v_bfe_u32 v72, v150, 4, 2
	v_and_b32_e32 v65, 12, v65
	v_bfe_u32 v74, v150, 2, 2
	v_lshlrev_b32_e32 v73, 8, v61
	v_bitop3_b32 v75, v65, v72, v74 bitop3:0x36
	v_lshl_or_b32 v108, v75, 4, v73
	v_or_b32_e32 v75, 4, v72
	v_bitop3_b32 v75, v65, v75, v74 bitop3:0x36
	v_lshl_or_b32 v109, v75, 4, v73
	v_or_b32_e32 v75, 8, v72
	v_bitop3_b32 v75, v65, v75, v74 bitop3:0x36
	v_lshl_or_b32 v110, v75, 4, v73
	v_or_b32_e32 v75, 12, v72
	v_ashrrev_i32_e32 v49, 6, v150
	v_bitop3_b32 v65, v65, v75, v74 bitop3:0x36
	v_lshl_or_b32 v111, v65, 4, v73
	v_and_b32_e32 v65, 0x7fffffc, v49
	v_or_b32_e32 v76, 1, v65
	v_bfe_u32 v73, v150, 1, 1
	v_lshlrev_b32_e32 v74, 6, v150
	v_and_or_b32 v75, v150, 12, v72
	v_and_b32_e32 v66, 8, v66
	v_lshlrev_b32_e32 v77, 1, v76
	v_or_b32_e32 v78, 2, v65
	v_or_b32_e32 v80, 3, v65
	v_and_or_b32 v66, v74, s92, v66
	v_lshlrev_b32_e32 v74, 1, v65
	v_bitop3_b32 v77, v77, v75, v73 bitop3:0x36
	v_lshlrev_b32_e32 v79, 1, v78
	v_lshlrev_b32_e32 v81, 1, v80
	v_and_b32_e32 v71, 3, v49
	v_bitop3_b32 v74, v74, v75, v73 bitop3:0x36
	v_bitop3_b32 v79, v79, v75, v73 bitop3:0x36
	v_bitop3_b32 v73, v81, v75, v73 bitop3:0x36
	v_lshl_add_u32 v75, v77, 4, 0
	v_lshlrev_b32_e32 v77, 2, v72
	v_lshl_add_u32 v112, v71, 12, 0
	v_lshl_add_u32 v92, v79, 4, 0
	v_lshl_or_b32 v71, v71, 4, v61
	v_or_b32_e32 v79, 2, v77
	v_cmp_gt_u32_e64 s[50:51], v79, v71
	v_or_b32_e32 v79, 3, v77
	v_cmp_gt_u32_e64 s[52:53], v79, v71
	v_or_b32_e32 v79, 16, v77
	v_writelane_b32 v247, s18, 59
	v_cmp_gt_u32_e64 s[54:55], v79, v71
	v_or_b32_e32 v79, 17, v77
	v_writelane_b32 v247, s19, 60
	v_cmp_gt_u32_e64 s[56:57], v79, v71
	v_or_b32_e32 v79, 18, v77
	v_writelane_b32 v247, s94, 61
	s_add_i32 s8, s94, 4
	s_mov_b32 s0, s84
	v_cmp_gt_u32_e64 s[58:59], v79, v71
	v_or_b32_e32 v79, 19, v77
	s_cmp_gt_u32 s8, 10
	v_writelane_b32 v247, s0, 62
	v_cmp_gt_u32_e64 s[60:61], v79, v71
	v_or_b32_e32 v79, 32, v77
	s_cselect_b64 s[18:19], -1, 0
	v_writelane_b32 v247, s1, 63
	s_lshl_b32 s0, s84, 7
	v_cmp_gt_u32_e64 s[62:63], v79, v71
	v_or_b32_e32 v79, 33, v77
	s_ashr_i32 s1, s0, 31
	v_cmp_gt_u32_e64 s[64:65], v79, v71
	v_or_b32_e32 v79, 34, v77
; __device__ __forceinline__ unsigned row_addr(int lane, int s) { return off_b((unsigned)(lane & 15), (unsigned)(4 * s + (lane >> 4))); }
; __device__ __forceinline__ f32x4 mfma16(bf16x8 a, bf16x8 b, f32x4 c) { return __builtin_amdgcn_mfma_f32_16x16x32_bf16(a, b, c, 0, 0, 0); }
; template <int DK, bool ISC> ...
;     ...
;     const int tb = w & 3, vh = w >> 2, g = lane >> 4, c15 = lane & 15, t = 16 * tb + c15;
;     unsigned ra[KS];
; #pragma unroll
;     for (int kk = 0; kk < KS; ++kk) ra[kk] = row_addr(lane, kk);
;     bf16x8 qf[KS], qif[KS];
; #pragma unroll
;     for (int kk = 0; kk < KS; ++kk) qf[kk] = row_frag_a(qs, ra[kk], tb);
;     f32x4 accs[4];
; #pragma unroll
;     for (int sb = 0; sb < 4; ++sb) accs[sb] = (f32x4){0.f, 0.f, 0.f, 0.f};
;     {   bf16x8 kf[2][4];
; #pragma unroll
;         for (int sb = 0; sb < 4; ++sb) kf[0][sb] = row_frag_a(ks, ra[0], sb);
; #pragma unroll
;         for (int kk = 0; kk < KS; ++kk) {
;             if (kk + 1 < KS) {
; #pragma unroll
;                 for (int sb = 0; sb < 4; ++sb) kf[(kk + 1) & 1][sb] = row_frag_a(ks, ra[kk + 1 < KS ? kk + 1 : 0], sb); }
; #pragma unroll
;             for (int sb = 0; sb < 4; ++sb) accs[sb] = mfma16(kf[kk & 1][sb], qf[kk], accs[sb]); } }
; #pragma unroll
;     for (int kk = 0; kk < KS; ++kk) qif[kk] = row_frag_a(qi, ra[kk], tb);
;     unsigned va[4];
; #pragma unroll
;     for (int i = 0; i < 4; ++i) va[i] = tr_addr<true>(lane, vh * 4 + i);
;     constexpr int NS = 2 + KS;
;     bf16x8 fa[2][4];
; #pragma unroll
;     for (int i = 0; i < 4; ++i) fa[0][i] = tr_frag_a<true>(vt, va[i], 0);
; #pragma unroll
;     for (int sb = 0; sb < 4; ++sb)
; #pragma unroll
;         for (int r = 0; r < 4; ++r) { const int s = 16 * sb + 4 * g + r; float v = accs[sb][r];
;             if (ISC) v *= exp2f(gl2 * (float)(t - s));
;             accs[sb][r] = (s <= t) ? v : 0.f; }
	v_or_b32_e32 v81, 49, v77
	v_and_b32_e32 v83, 64, v184
	s_cmp_lt_u32 s8, 11
	v_cmp_gt_u32_e64 s[66:67], v79, v71
	v_or_b32_e32 v79, 35, v77
	v_cmp_gt_u32_e64 s[8:9], v81, v71
	v_or_b32_e32 v81, 50, v77
	v_xor_b32_e32 v82, 16, v184
	v_add_u32_e32 v83, 64, v83
	v_readlane_b32 s14, v247, 6
	v_lshlrev_b32_e32 v105, 1, v58
	v_lshl_add_u32 v106, v58, 3, s74
	s_cselect_b32 s12, s93, 0x33984000
	v_cmp_gt_u32_e64 s[68:69], v79, v71
	v_or_b32_e32 v79, 48, v77
	v_cmp_gt_u32_e64 s[72:73], v81, v71
	v_or_b32_e32 v81, 51, v77
	v_cmp_lt_i32_e32 vcc, v82, v83
	v_cmp_gt_u32_e64 s[78:79], 16, v58
	v_lshl_add_u32 v121, v71, 2, s14
	v_lshlrev_b32_e32 v58, 8, v71
	s_add_i32 s14, 0, 0x18000
	v_lshlrev_b32_e32 v72, 3, v72
	v_cmp_gt_u32_e64 s[46:47], v77, v71
	v_cmp_lt_u32_e64 s[48:49], v77, v71
	v_cmp_gt_u32_e64 s[70:71], v79, v71
	v_cmp_gt_u32_e64 s[76:77], v81, v71
	v_cndmask_b32_e32 v82, v184, v82, vcc
	v_add3_u32 v72, s14, v58, v72
	v_lshlrev_b32_e32 v58, 11, v71
	v_lshlrev_b32_e32 v71, 4, v150
	v_lshlrev_b32_e32 v119, 2, v82
	v_xor_b32_e32 v82, 32, v184
	v_lshlrev_b32_e32 v95, 5, v80
	v_and_b32_e32 v80, 0xffffff00, v71
	v_lshlrev_b32_e32 v60, 4, v60
	v_and_b32_e32 v81, -4, v49
	v_cmp_lt_i32_e32 vcc, v82, v83
	v_add_u32_e32 v96, 0, v80
	v_add_u32_e32 v99, s14, v80
	v_and_b32_e32 v80, 0xffffff00, v60
	v_ashrrev_i32_e32 v62, 4, v62
	v_lshlrev_b32_e32 v114, 12, v81
	v_cndmask_b32_e32 v82, v184, v82, vcc
	v_lshlrev_b32_e32 v93, 5, v76
	v_lshl_or_b32 v76, v81, 4, v77
	v_lshlrev_b32_e32 v81, 2, v102
	v_add_u32_e32 v100, 0, v80
	v_add_u32_e32 v136, s14, v80
	v_lshlrev_b32_e32 v80, 2, v62
	v_lshlrev_b32_e32 v120, 2, v82
	v_and_b32_e32 v81, 12, v81
	v_bfe_u32 v82, v102, 2, 2
	v_lshlrev_b32_e32 v156, 8, v62
	v_and_b32_e32 v80, 12, v80
	v_bfe_u32 v62, v62, 2, 2
	v_ashrrev_i32_e32 v64, 4, v64
	v_bitop3_b32 v81, v81, v61, v82 bitop3:0x36
	v_lshlrev_b32_e32 v82, 2, v104
	v_bitop3_b32 v62, v80, v61, v62 bitop3:0x36
	v_lshlrev_b32_e32 v80, 2, v64
	v_lshlrev_b32_e32 v68, 3, v49
	v_and_b32_e32 v82, 12, v82
	v_bfe_u32 v83, v104, 2, 2
	v_lshlrev_b32_e32 v157, 8, v64
	v_and_b32_e32 v80, 12, v80
	v_bfe_u32 v64, v64, 2, 2
	s_add_i32 s13, 0, 0x10000
	v_bitop3_b32 v82, v82, v61, v83 bitop3:0x36
	v_bitop3_b32 v61, v80, v61, v64 bitop3:0x36
	v_lshlrev_b32_e32 v64, 1, v49
	v_or_b32_e32 v83, 4, v68
	s_lshl_b64 s[0:1], s[0:1], 2
	v_bfe_u32 v69, v150, 2, 4
	v_lshlrev_b32_e32 v81, 4, v81
	v_lshlrev_b32_e32 v82, 4, v82
	v_and_b32_e32 v80, 2, v64
	v_lshlrev_b32_e32 v84, 8, v83
	v_lshrrev_b32_e32 v83, 2, v83
	s_add_u32 s0, s10, s0
	v_lshlrev_b32_e32 v94, 5, v78
	v_lshl_or_b32 v78, v49, 4, v79
	v_add_u32_e32 v98, 0, v81
	v_add_u32_e32 v127, 0, v82
	v_add_u32_e32 v153, s13, v81
	v_add_u32_e32 v154, s13, v82
	v_bitop3_b32 v81, v80, v69, 4 bitop3:0x36
	v_bitop3_b32 v82, v80, v69, 8 bitop3:0x36
	v_bitop3_b32 v80, v80, v69, 12 bitop3:0x36
	v_bitop3_b32 v83, v83, v69, 3 bitop3:0x6c
	s_addc_u32 s1, s11, s1
	v_lshlrev_b32_e32 v63, 11, v49
	v_ashrrev_i32_e32 v77, 31, v76
	v_ashrrev_i32_e32 v79, 31, v78
	v_lshlrev_b32_e32 v81, 4, v81
	v_lshlrev_b32_e32 v82, 4, v82
	v_lshlrev_b32_e32 v80, 4, v80
	v_lshlrev_b32_e32 v83, 4, v83
	s_add_u32 s38, s4, s12
	v_add3_u32 v161, 0, v81, v63
	v_add3_u32 v162, 0, v82, v63
	v_add3_u32 v163, 0, v80, v63
	v_add3_u32 v164, 0, v83, v84
	v_or_b32_e32 v85, 5, v68
	v_or_b32_e32 v87, 6, v68
	v_or_b32_e32 v68, 7, v68
	v_or_b32_e32 v192, v83, v84
	v_or_b32_e32 v193, v80, v63
	v_or_b32_e32 v194, v82, v63
	v_or_b32_e32 v195, v81, v63
	s_addc_u32 s28, s5, 0
	v_lshl_add_u64 v[80:81], v[76:77], 2, s[0:1]
	v_lshl_add_u64 v[82:83], v[78:79], 2, s[0:1]
	v_readlane_b32 s0, v248, 45
	v_lshlrev_b32_e32 v86, 8, v85
	v_bfe_u32 v85, v85, 2, 2
	v_lshlrev_b32_e32 v88, 8, v87
	v_bfe_u32 v87, v87, 2, 2
	v_lshlrev_b32_e32 v89, 8, v68
	v_bfe_u32 v68, v68, 2, 2
	s_add_u32 s12, s0, s36
	v_readlane_b32 s0, v248, 46
	v_add_u32_e32 v113, s13, v108
	v_add_u32_e32 v116, s13, v109
	v_add_u32_e32 v117, s13, v110
	v_add_u32_e32 v118, s13, v111
	v_lshl_add_u32 v62, v62, 4, s13
	v_lshl_add_u32 v61, v61, 4, s13
	v_bitop3_b32 v85, v85, v69, 4 bitop3:0x36
	v_bitop3_b32 v87, v87, v69, 8 bitop3:0x36
	v_bitop3_b32 v68, v68, v69, 12 bitop3:0x36
	s_addc_u32 s13, s0, s37
	v_readlane_b32 s0, v248, 59
	v_lshlrev_b32_e32 v85, 4, v85
	v_lshlrev_b32_e32 v87, 4, v87
	v_lshlrev_b32_e32 v68, 4, v68
	s_mov_b64 s[10:11], 0x2ac00000
	v_readlane_b32 s1, v248, 60
	v_lshlrev_b32_e32 v59, 2, v150
	v_bitop3_b32 v64, v64, v69, 2 bitop3:0x6c
	v_add3_u32 v165, 0, v85, v86
	v_add3_u32 v166, 0, v87, v88
	v_add3_u32 v69, 0, v68, v89
	v_or_b32_e32 v68, v68, v89
	v_or_b32_e32 v190, v87, v88
	v_or_b32_e32 v191, v85, v86
	v_lshl_add_u64 v[84:85], v[52:53], 0, s[10:11]
	v_lshl_add_u64 v[86:87], v[50:51], 0, s[10:11]
	v_lshl_add_u64 v[88:89], v[54:55], 0, s[10:11]
	v_lshl_add_u64 v[90:91], v[56:57], 0, s[10:11]
	s_mov_b32 s11, s0
	v_cmp_gt_i32_e64 s[0:1], 7, v49
	v_and_b32_e32 v70, 12, v59
	v_lshlrev_b32_e32 v64, 4, v64
	v_writelane_b32 v246, s0, 0
	v_add_u32_e32 v59, 0, v70
	v_lshl_add_u32 v74, v74, 4, 0
	v_lshl_add_u32 v73, v73, 4, 0
	v_lshlrev_b32_e32 v65, 5, v65
	v_and_b32_e32 v71, 0xf0, v71
	v_lshlrev_b32_e32 v97, 8, v102
	v_and_b32_e32 v60, 0xf0, v60
	v_lshlrev_b32_e32 v101, 8, v104
	v_add3_u32 v160, 0, v64, v63
	v_or_b32_e32 v64, v64, v63
	v_writelane_b32 v246, s1, 1
	v_cmp_gt_i32_e64 s[0:1], 8, v49
	v_lshl_add_u32 v107, v49, 9, v106
	v_cmp_gt_i32_e64 s[40:41], 4, v49
	v_lshl_or_b32 v115, v49, 12, v183
	v_add_u32_e32 v122, v121, v103
	v_cmp_gt_i32_e64 s[2:3], 1, v49
	v_cmp_gt_i32_e64 s[80:81], 0, v49
	v_add_u32_e32 v123, v96, v71
	v_add_u32_e32 v124, v98, v97
	v_add_u32_e32 v125, v99, v71
	v_add_u32_e32 v126, v100, v60
; __device__ __forceinline__ unsigned cvt_pk_bf16(float lo, float hi) { const f32x2 f = {lo, hi}; const bf16x2_t v = __builtin_convertvector(f, bf16x2_t); return __builtin_bit_cast(unsigned, v); }
; __device__ __forceinline__ float bflo(unsigned u) { return __uint_as_float(u << 16); }
; __device__ __forceinline__ float bfhi(unsigned u) { return __uint_as_float(u & 0xffff0000u); }
; __device__ __forceinline__ float rcp_f(float v) { return __builtin_amdgcn_rcpf(v); }
; __device__ __forceinline__ float silu_f(float v) { return v * rcp_f(1.f + __expf(-v)); }
; template <int DK, bool ISC> ...
;     ...
;     const float rinv = rsqrtf((red[t] + red[64 + t]) * (1.f / 128.f) + EPSN);
; #pragma unroll
;     for (int i = 0; i < 4; ++i) { const int v0 = 16 * (vh * 4 + i) + 4 * g;
;         const u32x2 gt2 = gtv[i];
;         f32x4 gn = (f32x4){1.f, 1.f, 1.f, 1.f}; if (!ISC) gn = *(const f32x4*)(gain + v0);
;         const float o0 = acco[i][0] * rinv * gn[0] * silu_f(bflo(gt2.x)), o1 = acco[i][1] * rinv * gn[1] * silu_f(bfhi(gt2.x));
;         const float o2 = acco[i][2] * rinv * gn[2] * silu_f(bflo(gt2.y)), o3 = acco[i][3] * rinv * gn[3] * silu_f(bfhi(gt2.y));
;         u32x2 o; o.x = cvt_pk_bf16(o0, o1); o.y = cvt_pk_bf16(o2, o3);
;         *(u32x2*)(y + (size_t)t * DM + v0) = o; }
; __device__ __forceinline__ float lb_of(const Params& P, int layer, int k) {
;     if (layer == 0) return 0.f;
;     const float l0 = P.lb_logits[k], l1 = P.lb_logits[768 + k];
;     return rcp_f(1.f + __expf(l0 - l1));
	v_add_u32_e32 v127, v127, v101
	v_add_u32_e32 v152, v136, v60
	v_add_u32_e32 v153, v153, v97
	v_add_u32_e32 v154, v154, v101
	v_add_u32_e32 v156, v62, v156
	v_add_u32_e32 v157, v61, v157
	v_lshlrev_b32_e32 v158, 1, v48
	v_add_u32_e32 v159, v67, v63
	v_add_u32_e32 v160, v160, v70
	v_add_u32_e32 v161, v161, v70
	v_add_u32_e32 v162, v162, v70
	v_add_u32_e32 v163, v163, v70
	v_add_u32_e32 v164, v164, v70
	v_add_u32_e32 v165, v165, v70
	v_add_u32_e32 v166, v166, v70
	v_add_u32_e32 v167, v69, v70
	v_add_u32_e32 v168, v74, v66
	v_add_u32_e32 v169, v75, v66
	v_add_u32_e32 v170, v92, v66
	v_add_u32_e32 v171, v73, v66
	v_add_u32_e32 v172, v72, v65
	v_add_u32_e32 v173, v72, v93
	v_add_u32_e32 v174, v72, v94
	v_add_u32_e32 v175, v72, v95
	v_lshlrev_b32_e32 v136, 1, v58
	v_add_u32_e32 v189, v59, v68
	v_add_u32_e32 v190, v59, v190
	v_add_u32_e32 v191, v59, v191
	v_add_u32_e32 v192, v59, v192
	v_add_u32_e32 v193, v59, v193
	v_add_u32_e32 v194, v59, v194
	v_add_u32_e32 v195, v59, v195
	v_add_u32_e32 v196, v59, v64
	s_mov_b32 s10, s89
	v_cmp_gt_i32_e64 s[82:83], 2, v49
	v_cmp_lt_i32_e64 s[86:87], 0, v49
	v_cmp_gt_i32_e64 s[84:85], 3, v49
	v_cmp_lt_i32_e64 s[92:93], 1, v49
	v_cmp_gt_i32_e64 s[88:89], 5, v49
	v_cmp_gt_i32_e64 s[90:91], 6, v49
	v_writelane_b32 v246, s0, 2
	s_nop 1
	v_writelane_b32 v246, s1, 3
	global_load_dwordx4 v[222:225], v[80:81], off
	global_load_dwordx4 v[226:229], v[80:81], off offset:64
	global_load_dwordx4 v[236:239], v[80:81], off offset:128
	global_load_dwordx4 v[240:243], v[82:83], off
	s_cmp_eq_u32 s18, 0
	s_cbranch_scc1 .Llb3_pre_skip
	s_mul_hi_i32 s14, s11, 0x2aaaaaab
	s_lshr_b32 s15, s14, 31
	s_add_i32 s14, s14, s15
	s_mul_i32 s14, s14, 0xfffffd00
	s_add_i32 s14, s14, s10
	v_add_u32_e32 v230, s14, v105
	v_ashrrev_i32_e32 v231, 31, v230
	v_lshl_add_u64 v[230:231], v[230:231], 2, s[16:17]
	global_load_dwordx2 v[244:245], v[230:231], off offset:3072
	global_load_dwordx2 v[230:231], v[230:231], off
.Llb3_pre_skip:
	s_waitcnt vmcnt(0)
	s_branch .LBB0_106
.LBB0_105:
	s_or_b64 exec, exec, vcc
	ds_read_b64 v[74:75], v172
	ds_read_b64 v[72:73], v173
	ds_read_b64 v[70:71], v174
	ds_read_b64 v[66:67], v175
	s_waitcnt lgkmcnt(0)
	s_barrier
	s_lshl_b32 s42, s15, 6
	ds_read2st64_b32 v[64:65], v121 offset1:1
	s_ashr_i32 s43, s42, 31
	s_lshl_b64 s[42:43], s[42:43], 12
	s_add_u32 s42, s38, s42
	s_addc_u32 s43, s28, s43
	s_ashr_i32 s15, s14, 31
	s_lshl_b64 s[14:15], s[14:15], 1
	s_waitcnt lgkmcnt(0)
	v_add_f32_e32 v64, v64, v65
	s_add_u32 s14, s42, s14
	v_fmamk_f32 v64, v64, 0x3c000000, v181
	s_mov_b32 s42, 0x800000
	v_cmp_gt_f32_e32 vcc, s42, v64
	v_mul_f32_e32 v65, 0x4b800000, v64
	v_lshlrev_b32_e32 v96, 16, v74
	v_cndmask_b32_e32 v64, v64, v65, vcc
	v_rsq_f32_e32 v64, v64
	v_mul_f32_e32 v69, 0xbfb8aa3b, v96
	v_exp_f32_e32 v69, v69
	v_and_b32_e32 v97, 0xffff0000, v74
	v_mul_f32_e32 v65, 0x45800000, v64
	v_cndmask_b32_e32 v68, v64, v65, vcc
	v_add_f32_e32 v69, 1.0, v69
	v_rcp_f32_e32 v98, v69
	v_pk_mul_f32 v[60:61], v[60:61], v[68:69] op_sel_hi:[1,0]
	v_mul_f32_e32 v69, 0xbfb8aa3b, v97
	v_exp_f32_e32 v69, v69
	v_lshlrev_b32_e32 v74, 16, v75
	v_and_b32_e32 v75, 0xffff0000, v75
	s_addc_u32 s15, s43, s15
	v_add_f32_e32 v69, 1.0, v69
	v_rcp_f32_e32 v99, v69
	v_mul_f32_e32 v69, 0xbfb8aa3b, v74
	v_exp_f32_e32 v69, v69
	v_lshl_add_u64 v[64:65], s[14:15], 0, v[136:137]
	v_readlane_b32 s14, v248, 36
	s_add_i32 s10, s10, s14
	v_add_f32_e32 v69, 1.0, v69
	v_pk_mul_f32 v[62:63], v[62:63], v[68:69] op_sel_hi:[1,0]
	v_readlane_b32 s14, v248, 47
	v_readlane_b32 s15, v248, 48
	s_add_u32 s12, s12, s14
	s_addc_u32 s13, s13, s15
	s_andn2_b64 vcc, exec, s[0:1]
	v_pk_mul_f32 v[60:61], v[222:223], v[60:61]
	v_pk_mul_f32 v[92:93], v[98:99], v[96:97]
	v_pk_mul_f32 v[62:63], v[224:225], v[62:63]
	v_pk_mul_f32 v[60:61], v[92:93], v[60:61]
	v_rcp_f32_e32 v92, v69
	v_mul_f32_e32 v69, 0xbfb8aa3b, v75
	v_exp_f32_e32 v69, v69
	s_nop 0
	v_add_f32_e32 v69, 1.0, v69
	v_rcp_f32_e32 v93, v69
	s_nop 0
	v_pk_mul_f32 v[74:75], v[92:93], v[74:75]
	s_nop 0
	v_pk_mul_f32 v[62:63], v[74:75], v[62:63]
	v_cvt_pk_bf16_f32 v74, v60, v61
	v_cvt_pk_bf16_f32 v75, v62, v63
	v_lshl_add_u64 v[60:61], v[76:77], 1, v[64:65]
	s_cmp_eq_u32 s18, 0
	s_cbranch_scc1 .Llb3_tail_skip
	s_mul_hi_i32 s14, s11, 0x2aaaaaab
	s_lshr_b32 s15, s14, 31
	s_add_i32 s14, s14, s15
	s_mul_i32 s14, s14, 0xfffffd00
	s_add_i32 s14, s14, s10
	v_add_u32_e32 v230, s14, v105
	v_ashrrev_i32_e32 v231, 31, v230
	v_lshl_add_u64 v[230:231], v[230:231], 2, s[16:17]
	global_load_dwordx2 v[244:245], v[230:231], off offset:3072
	global_load_dwordx2 v[230:231], v[230:231], off
; __device__ __forceinline__ unsigned cvt_pk_bf16(float lo, float hi) { const f32x2 f = {lo, hi}; const bf16x2_t v = __builtin_convertvector(f, bf16x2_t); return __builtin_bit_cast(unsigned, v); }
; __device__ __forceinline__ float bflo(unsigned u) { return __uint_as_float(u << 16); }
; __device__ __forceinline__ float bfhi(unsigned u) { return __uint_as_float(u & 0xffff0000u); }
; __device__ __forceinline__ float rcp_f(float v) { return __builtin_amdgcn_rcpf(v); }
; __device__ __forceinline__ float silu_f(float v) { return v * rcp_f(1.f + __expf(-v)); }
; template <int DK, bool ISC> ...
;     ...
;     const float rinv = rsqrtf((red[t] + red[64 + t]) * (1.f / 128.f) + EPSN);
; #pragma unroll
;     for (int i = 0; i < 4; ++i) { const int v0 = 16 * (vh * 4 + i) + 4 * g;
;         const u32x2 gt2 = gtv[i];
;         f32x4 gn = (f32x4){1.f, 1.f, 1.f, 1.f}; if (!ISC) gn = *(const f32x4*)(gain + v0);
;         const float o0 = acco[i][0] * rinv * gn[0] * silu_f(bflo(gt2.x)), o1 = acco[i][1] * rinv * gn[1] * silu_f(bfhi(gt2.x));
;         const float o2 = acco[i][2] * rinv * gn[2] * silu_f(bflo(gt2.y)), o3 = acco[i][3] * rinv * gn[3] * silu_f(bfhi(gt2.y));
;         u32x2 o; o.x = cvt_pk_bf16(o0, o1); o.y = cvt_pk_bf16(o2, o3);
;         *(u32x2*)(y + (size_t)t * DM + v0) = o; }
; __device__ __forceinline__ float lb_of(const Params& P, int layer, int k) {
;     if (layer == 0) return 0.f;
;     const float l0 = P.lb_logits[k], l1 = P.lb_logits[768 + k];
;     return rcp_f(1.f + __expf(l0 - l1));
.Llb3_tail_skip:
	global_store_dwordx2 v[60:61], v[74:75], off
	v_lshlrev_b32_e32 v62, 16, v72
	v_mul_f32_e32 v69, 0xbfb8aa3b, v62
	v_exp_f32_e32 v69, v69
	v_and_b32_e32 v63, 0xffff0000, v72
	v_add_f32_e32 v69, 1.0, v69
	v_rcp_f32_e32 v74, v69
	v_pk_mul_f32 v[56:57], v[56:57], v[68:69] op_sel_hi:[1,0]
	v_mul_f32_e32 v69, 0xbfb8aa3b, v63
	v_exp_f32_e32 v69, v69
	v_pk_mul_f32 v[56:57], v[226:227], v[56:57]
	v_add_f32_e32 v69, 1.0, v69
	v_rcp_f32_e32 v75, v69
	s_nop 0
	v_pk_mul_f32 v[62:63], v[74:75], v[62:63]
	s_nop 0
	v_pk_mul_f32 v[56:57], v[62:63], v[56:57]
	v_lshlrev_b32_e32 v62, 16, v73
	v_mul_f32_e32 v69, 0xbfb8aa3b, v62
	v_exp_f32_e32 v69, v69
	v_and_b32_e32 v63, 0xffff0000, v73
	v_cvt_pk_bf16_f32 v56, v56, v57
	v_add_f32_e32 v69, 1.0, v69
	v_rcp_f32_e32 v72, v69
	v_pk_mul_f32 v[58:59], v[58:59], v[68:69] op_sel_hi:[1,0]
	v_mul_f32_e32 v69, 0xbfb8aa3b, v63
	v_exp_f32_e32 v69, v69
	v_pk_mul_f32 v[58:59], v[228:229], v[58:59]
	v_add_f32_e32 v69, 1.0, v69
	v_rcp_f32_e32 v73, v69
	s_nop 0
	v_pk_mul_f32 v[62:63], v[72:73], v[62:63]
	s_nop 0
	v_pk_mul_f32 v[58:59], v[62:63], v[58:59]
	v_lshlrev_b32_e32 v62, 16, v70
	v_cvt_pk_bf16_f32 v57, v58, v59
	global_store_dwordx2 v[60:61], v[56:57], off offset:32
	v_mul_f32_e32 v69, 0xbfb8aa3b, v62
	v_exp_f32_e32 v69, v69
	v_and_b32_e32 v63, 0xffff0000, v70
	v_add_f32_e32 v69, 1.0, v69
	v_pk_mul_f32 v[52:53], v[52:53], v[68:69] op_sel_hi:[1,0]
	v_rcp_f32_e32 v72, v69
	v_pk_mul_f32 v[54:55], v[54:55], v[68:69] op_sel_hi:[1,0]
	v_pk_mul_f32 v[48:49], v[48:49], v[68:69] op_sel_hi:[1,0]
	v_pk_mul_f32 v[50:51], v[50:51], v[68:69] op_sel_hi:[1,0]
	v_pk_mul_f32 v[52:53], v[236:237], v[52:53]
	v_mul_f32_e32 v56, 0xbfb8aa3b, v63
	v_exp_f32_e32 v56, v56
	v_pk_mul_f32 v[54:55], v[238:239], v[54:55]
	v_add_f32_e32 v56, 1.0, v56
	v_rcp_f32_e32 v73, v56
	s_nop 0
	v_pk_mul_f32 v[56:57], v[72:73], v[62:63]
	s_nop 0
	v_pk_mul_f32 v[52:53], v[56:57], v[52:53]
	v_lshlrev_b32_e32 v56, 16, v71
	v_and_b32_e32 v57, 0xffff0000, v71
	v_mul_f32_e32 v62, 0xbfb8aa3b, v56
	v_mul_f32_e32 v58, 0xbfb8aa3b, v57
	v_exp_f32_e32 v62, v62
	v_exp_f32_e32 v58, v58
	v_cvt_pk_bf16_f32 v52, v52, v53
	v_add_f32_e32 v62, 1.0, v62
	v_add_f32_e32 v58, 1.0, v58
	v_rcp_f32_e32 v62, v62
	v_rcp_f32_e32 v63, v58
	s_nop 0
	v_pk_mul_f32 v[56:57], v[62:63], v[56:57]
	s_nop 0
	v_pk_mul_f32 v[54:55], v[56:57], v[54:55]
	v_lshlrev_b32_e32 v56, 16, v66
	v_cvt_pk_bf16_f32 v53, v54, v55
	global_store_dwordx2 v[60:61], v[52:53], off offset:64
	v_and_b32_e32 v57, 0xffff0000, v66
	v_mul_f32_e32 v58, 0xbfb8aa3b, v56
	v_exp_f32_e32 v58, v58
	v_pk_mul_f32 v[48:49], v[240:241], v[48:49]
	v_mul_f32_e32 v52, 0xbfb8aa3b, v57
	v_exp_f32_e32 v52, v52
	v_add_f32_e32 v58, 1.0, v58
	v_rcp_f32_e32 v58, v58
	v_pk_mul_f32 v[50:51], v[242:243], v[50:51]
	v_add_f32_e32 v52, 1.0, v52
	v_rcp_f32_e32 v59, v52
	s_nop 0
	v_pk_mul_f32 v[52:53], v[58:59], v[56:57]
	s_nop 0
	v_pk_mul_f32 v[48:49], v[52:53], v[48:49]
	v_lshlrev_b32_e32 v52, 16, v67
	v_and_b32_e32 v53, 0xffff0000, v67
	v_mul_f32_e32 v56, 0xbfb8aa3b, v52
	v_mul_f32_e32 v54, 0xbfb8aa3b, v53
	v_exp_f32_e32 v56, v56
	v_exp_f32_e32 v54, v54
	v_cvt_pk_bf16_f32 v48, v48, v49
	v_add_f32_e32 v56, 1.0, v56
	v_add_f32_e32 v54, 1.0, v54
	v_rcp_f32_e32 v56, v56
	v_rcp_f32_e32 v57, v54
	s_nop 0
	v_pk_mul_f32 v[52:53], v[56:57], v[52:53]
	s_nop 0
	v_pk_mul_f32 v[50:51], v[52:53], v[50:51]
	s_nop 0
	v_cvt_pk_bf16_f32 v49, v50, v51
	v_lshl_add_u64 v[50:51], v[78:79], 1, v[64:65]
	global_store_dwordx2 v[50:51], v[48:49], off
	s_cbranch_vccz .LBB0_118
.LBB0_106:
	s_mul_hi_i32 s15, s11, 0x2aaaaaab
	s_lshr_b32 s0, s15, 31
	s_add_i32 s15, s15, s0
	s_mul_i32 s0, s15, 0xfffffd00
	s_add_i32 s14, s0, s10
	v_add_u32_e32 v50, s14, v105
	v_cndmask_b32_e64 v48, 0, 1, s[18:19]
	v_mov_b32_e32 v49, 0
	v_cmp_ne_u32_e64 s[0:1], 1, v48
	s_andn2_b64 vcc, exec, s[18:19]
	v_ashrrev_i32_e32 v51, 31, v50
	v_mov_b32_e32 v48, 0
	s_cbranch_vccnz .LBB0_108
	s_waitcnt vmcnt(4)
	v_sub_f32_e32 v48, v230, v244
	v_mul_f32_e32 v48, 0x3fb8aa3b, v48
	v_exp_f32_e32 v48, v48
	s_nop 0
	v_add_f32_e32 v48, 1.0, v48
	v_rcp_f32_e32 v48, v48
.LBB0_108:
	s_and_b64 vcc, exec, s[0:1]
	s_cbranch_vccnz .LBB0_110
	v_sub_f32_e32 v49, v231, v245
	v_mul_f32_e32 v49, 0x3fb8aa3b, v49
	v_exp_f32_e32 v49, v49
	s_nop 0
	v_add_f32_e32 v49, 1.0, v49
	v_rcp_f32_e32 v49, v49
; __device__ __forceinline__ void swz_put(LAS unsigned char* reg, int i, u32x4 v) { *(LAS u32x4*)(reg + off_b((unsigned)(i >> 4), (unsigned)(i & 15))) = v; }
; __device__ __forceinline__ void a3_phase(const Params& P, int layer, LAS unsigned char* lds, int tid) {
;     ...
;     for (; it < 3072; it += G) {
;         const int cidx = it / 6, h = it % 6, tok0 = cidx * 64;
;         const float lb0 = lb_of(P, layer, h * 128 + 2 * kp), lb1 = lb_of(P, layer, h * 128 + 2 * kp + 1), om0 = 1.f - lb0, om1 = 1.f - lb1;
; #pragma unroll
;         for (int u = 0; u < 2; ++u) { const int i = tid + 512 * u; raw_put(lds + R_Z, i, R.z[u]); raw_put(lds + R_Q, i, R.q[u]); swz_put(lds + R_V, i, R.v[u]); raw_put(lds + R_G, i, R.g[u]); }
; #pragma unroll
;         for (int u = 0; u < 4; ++u) swz_put(lds + R_ST, tid + 512 * u, R.st[u]);
;         __syncthreads();
;         if (it + G < 3072) a3_load(R, P, it + G, tid);
.LBB0_110:
	s_add_i32 s11, s11, s26
	s_cmpk_gt_i32 s11, 0xbff
	s_cselect_b64 s[0:1], -1, 0
	s_and_b64 vcc, exec, s[0:1]
	s_waitcnt vmcnt(4)
	ds_write_b128 v123, v[0:3]
	ds_write_b128 v123, v[4:7] offset:16384
	ds_write_b128 v124, v[8:11] offset:49152
	ds_write_b128 v125, v[12:15]
	ds_write_b128 v126, v[16:19]
	ds_write_b128 v126, v[20:23] offset:16384
	ds_write_b128 v127, v[24:27] offset:49152
	ds_write_b128 v152, v[28:31]
	ds_write_b128 v153, v[32:35]
	ds_write_b128 v154, v[36:39]
	ds_write_b128 v156, v[40:43]
	ds_write_b128 v157, v[44:47]
	s_waitcnt lgkmcnt(0)
	s_barrier
	s_cbranch_vccnz .LBB0_112
	s_mul_hi_i32 s42, s11, 0x2aaaaaab
	s_lshr_b32 s43, s42, 31
	s_add_i32 s42, s42, s43
	s_mul_i32 s43, s42, -6
	s_add_i32 vcc_lo, s11, s43
	s_ashr_i32 vcc_hi, vcc_lo, 31
	s_mov_b32 s35, s28
	s_mov_b32 s28, s38
	s_mov_b64 s[38:39], s[92:93]
	s_mov_b64 s[92:93], s[82:83]
	s_mov_b64 s[82:83], s[2:3]
	s_mov_b64 s[2:3], s[78:79]
	s_mov_b64 s[78:79], s[72:73]
	s_mov_b64 s[72:73], s[68:69]
	s_mov_b64 s[68:69], s[64:65]
	s_mov_b64 s[64:65], s[60:61]
	s_mov_b64 s[60:61], s[56:57]
	s_mov_b64 s[56:57], s[52:53]
	s_mov_b64 s[52:53], s[48:49]
	s_lshl_b32 s48, s42, 6
	s_lshl_b64 vcc, vcc, 23
	v_readlane_b32 s42, v247, 53
	s_add_u32 s42, s42, vcc_lo
	v_readlane_b32 s43, v247, 54
	s_addc_u32 s43, s43, vcc_hi
	v_readlane_b32 s44, v247, 55
	s_add_u32 s44, s44, vcc_lo
	v_readlane_b32 s45, v247, 56
	s_addc_u32 s45, s45, vcc_hi
	s_mov_b64 s[94:95], s[76:77]
	s_mov_b64 s[76:77], s[18:19]
	s_mov_b64 s[18:19], s[6:7]
	s_mov_b64 s[6:7], s[16:17]
	s_mov_b64 s[16:17], s[8:9]
	s_mov_b64 s[8:9], s[70:71]
	s_mov_b64 s[70:71], s[66:67]
	s_mov_b64 s[66:67], s[62:63]
	s_mov_b64 s[62:63], s[58:59]
	s_mov_b64 s[58:59], s[54:55]
	s_mov_b64 s[54:55], s[50:51]
	s_mov_b64 s[50:51], s[46:47]
	v_readlane_b32 s46, v247, 57
	s_add_u32 s46, s46, vcc_lo
	v_readlane_b32 s47, v247, 58
	v_add_u32_e32 v0, s48, v102
	v_add_u32_e32 v16, s48, v104
	s_addc_u32 s47, s47, vcc_hi
	v_readlane_b32 s49, v247, 59
	v_ashrrev_i32_e32 v1, 31, v0
	v_ashrrev_i32_e32 v17, 31, v16
	s_add_u32 vcc_lo, s49, vcc_lo
	v_readlane_b32 s49, v247, 60
	v_lshlrev_b64 v[8:9], 8, v[0:1]
	v_lshlrev_b64 v[24:25], 8, v[16:17]
	s_addc_u32 vcc_hi, s49, vcc_hi
	v_or_b32_e32 v8, v8, v158
	v_or_b32_e32 v24, v24, v158
	v_lshl_add_u64 v[0:1], s[42:43], 0, v[8:9]
	v_lshl_add_u64 v[4:5], s[44:45], 0, v[8:9]
	v_lshl_add_u64 v[10:11], s[46:47], 0, v[8:9]
	v_lshl_add_u64 v[12:13], vcc, 0, v[8:9]
	v_lshl_add_u64 v[16:17], s[42:43], 0, v[24:25]
	v_lshl_add_u64 v[20:21], s[44:45], 0, v[24:25]
	v_lshl_add_u64 v[26:27], s[46:47], 0, v[24:25]
	v_lshl_add_u64 v[28:29], vcc, 0, v[24:25]
	v_lshl_add_u64 v[32:33], s[12:13], 0, v[84:85]
	v_lshl_add_u64 v[36:37], s[12:13], 0, v[86:87]
	v_lshl_add_u64 v[40:41], s[12:13], 0, v[88:89]
	v_lshl_add_u64 v[44:45], s[12:13], 0, v[90:91]
	global_load_dwordx4 v[0:3], v[0:1], off
	s_nop 0
	global_load_dwordx4 v[4:7], v[4:5], off
	s_nop 0
	global_load_dwordx4 v[8:11], v[10:11], off
	s_nop 0
	global_load_dwordx4 v[12:15], v[12:13], off
	s_nop 0
	global_load_dwordx4 v[16:19], v[16:17], off
	s_nop 0
	global_load_dwordx4 v[20:23], v[20:21], off
	s_nop 0
	global_load_dwordx4 v[24:27], v[26:27], off
	s_nop 0
	global_load_dwordx4 v[28:31], v[28:29], off
	s_nop 0
	global_load_dwordx4 v[32:35], v[32:33], off
	s_nop 0
	global_load_dwordx4 v[36:39], v[36:37], off
	s_nop 0
	global_load_dwordx4 v[40:43], v[40:41], off
	s_nop 0
	global_load_dwordx4 v[44:47], v[44:45], off
	s_mov_b64 s[48:49], s[52:53]
	s_mov_b64 s[52:53], s[56:57]
	s_mov_b64 s[56:57], s[60:61]
	s_mov_b64 s[60:61], s[64:65]
	s_mov_b64 s[64:65], s[68:69]
	s_mov_b64 s[68:69], s[72:73]
	s_mov_b64 s[72:73], s[78:79]
	s_mov_b64 s[78:79], s[2:3]
	s_mov_b64 s[2:3], s[82:83]
	s_mov_b64 s[82:83], s[92:93]
	s_mov_b64 s[92:93], s[38:39]
	s_mov_b32 s38, s28
	s_mov_b32 s28, s35
	s_mov_b64 s[46:47], s[50:51]
	s_mov_b64 s[50:51], s[54:55]
	s_mov_b64 s[54:55], s[58:59]
	s_mov_b64 s[58:59], s[62:63]
	s_mov_b64 s[62:63], s[66:67]
	s_mov_b64 s[66:67], s[70:71]
	s_mov_b64 s[70:71], s[8:9]
	s_mov_b64 s[8:9], s[16:17]
	s_mov_b64 s[16:17], s[6:7]
	s_mov_b64 s[6:7], s[18:19]
	s_mov_b64 s[18:19], s[76:77]
	s_mov_b64 s[76:77], s[94:95]
	s_mov_b32 s95, 0xc2fc0000

; #define LAS __attribute__((address_space(3)))
; __device__ __forceinline__ void a1_phase(const Params& P, int layer, LAS unsigned char* lds, int tid) {
;     const int w = tid >> 6, lane = tid & 63, kp = tid & 63, G = gridDim.x;
;     LAS float* part = (LAS float*)(lds + R_AUX);
;     A1Regs R; int it = blockIdx.x; if (it < 3072) a1_load(R, P, it, tid);
.LBB0_201:
	v_add_u32_e32 v16, 0x200, v150
	v_and_b32_e32 v46, 12, v150
	s_waitcnt vmcnt(0)
	v_lshrrev_b32_e32 v0, 3, v150
	v_lshlrev_b32_e32 v33, 4, v150
	s_andn2_b64 vcc, exec, s[0:1]
	v_lshlrev_b32_e32 v48, 3, v150
	v_and_b32_e32 v45, 15, v150
	v_ashrrev_i32_e32 v44, 4, v16
	v_and_or_b32 v47, v0, 2, v46
	v_and_b32_e32 v32, 0xf0, v33
	s_cbranch_vccnz .LBB0_216
; #define LAS __attribute__((address_space(3)))
; __device__ __forceinline__ void a1_load(A1Regs& R, const Params& P, int item, int tid) {
;     const int cidx = item / 6, h = item % 6; const bf16_t* proj = (const bf16_t*)(P.ws + WS_PROJ);
; #pragma unroll
;     for (int u = 0; u < 2; ++u) { const int i = tid + 512 * u; const size_t o = (size_t)(cidx * 64 + (i >> 4)) * 128 + (i & 15) * 8;
;         R.z[u] = *(const u32x4*)(pjp(proj, AF, 128, h, 0) + o); R.v[u] = *(const u32x4*)(pjp(proj, AI, 128, h, 0) + o); }
; }
; __device__ __forceinline__ void a1_phase(const Params& P, int layer, LAS unsigned char* lds, int tid) {
;     const int w = tid >> 6, lane = tid & 63, kp = tid & 63, G = gridDim.x;
;     LAS float* part = (LAS float*)(lds + R_AUX);
;     A1Regs R; int it = blockIdx.x; if (it < 3072) a1_load(R, P, it, tid);
	s_add_u32 s8, s4, 0xfc00000
	s_addc_u32 s9, s5, 0
	s_lshl_b64 s[0:1], s[90:91], 1
	s_add_u32 s12, s8, s0
	s_addc_u32 s13, s9, s1
	s_add_u32 s10, s4, 0x12c00000
	v_add_u32_e32 v0, s88, v49
	v_add_u32_e32 v8, s88, v44
	v_and_b32_e32 v18, 0x78, v48
	s_addc_u32 s11, s5, 0
	v_ashrrev_i32_e32 v1, 31, v0
	v_ashrrev_i32_e32 v9, 31, v8
	s_add_u32 s0, s10, s0
	v_lshlrev_b64 v[0:1], 8, v[0:1]
	v_lshlrev_b32_e32 v10, 1, v18
	v_lshlrev_b64 v[8:9], 8, v[8:9]
	s_addc_u32 s1, s11, s1
	v_or_b32_e32 v0, v0, v10
	v_or_b32_e32 v8, v8, v10
	v_lshl_add_u64 v[2:3], s[12:13], 0, v[0:1]
	v_lshl_add_u64 v[4:5], s[0:1], 0, v[0:1]
	v_lshl_add_u64 v[10:11], s[12:13], 0, v[8:9]
	v_lshl_add_u64 v[12:13], s[0:1], 0, v[8:9]
	global_load_dwordx4 v[0:3], v[2:3], off
	s_nop 0
	global_load_dwordx4 v[4:7], v[4:5], off
	s_nop 0
	global_load_dwordx4 v[8:11], v[10:11], off
	s_nop 0
	global_load_dwordx4 v[12:15], v[12:13], off
	v_lshlrev_b32_e32 v22, 2, v150
	v_and_b32_e32 v30, 12, v22
	v_bfe_u32 v22, v150, 1, 5
	v_and_b32_e32 v19, 63, v150
	v_ashrrev_i32_e32 v17, 6, v150
	v_bfe_u32 v29, v150, 2, 4
	v_and_b32_e32 v136, 24, v22
	v_lshlrev_b32_e32 v20, 3, v19
	v_and_or_b32 v22, v29, 3, v136
	v_lshlrev_b32_e32 v31, 1, v17
	v_bfe_u32 v24, v19, 1, 1
	v_bitop3_b32 v26, v24, v47, v31 bitop3:0x36
	v_and_b32_e32 v38, 8, v20
	v_or_b32_e32 v28, 4, v22
	v_lshl_add_u32 v22, v22, 8, 0
	v_bfe_u32 v34, v28, 2, 2
	v_lshl_add_u32 v39, v26, 4, v22
	v_add_u32_e32 v41, v22, v38
	v_or_b32_e32 v22, v24, v47
	v_lshlrev_b32_e32 v43, 4, v22
	v_bitop3_b32 v22, v34, v24, v46 bitop3:0x36
	v_lshlrev_b32_e32 v70, 4, v22
	v_or_b32_e32 v22, 2, v24
	v_bitop3_b32 v22, v34, v22, v46 bitop3:0x36
	v_lshlrev_b32_e32 v72, 4, v22
	v_or_b32_e32 v22, 4, v24
	v_bitop3_b32 v22, v34, v22, v46 bitop3:0x36
	v_lshlrev_b32_e32 v74, 4, v22
	v_or_b32_e32 v22, 6, v24
	v_bitop3_b32 v22, v34, v22, v46 bitop3:0x36
	v_lshlrev_b32_e32 v76, 4, v22
	v_or_b32_e32 v22, 8, v24
	v_bitop3_b32 v22, v34, v22, v46 bitop3:0x36
	v_lshlrev_b32_e32 v78, 4, v22
	v_or_b32_e32 v22, 10, v24
	v_bitop3_b32 v22, v34, v22, v46 bitop3:0x36
	v_lshlrev_b32_e32 v80, 4, v22
	v_or_b32_e32 v22, 12, v24
	v_bitop3_b32 v22, v34, v22, v46 bitop3:0x36
	v_or_b32_e32 v25, v24, v31
	v_lshlrev_b32_e32 v82, 4, v22
	v_or_b32_e32 v22, 14, v24
	v_bitop3_b32 v25, v34, v25, v46 bitop3:0x36
	v_bitop3_b32 v22, v34, v22, v46 bitop3:0x36
	v_and_b32_e32 v34, 0xffffff00, v33
	v_lshl_add_u32 v26, v28, 8, 0
	v_add_u32_e32 v53, 0, v34
	v_lshlrev_b32_e32 v34, 2, v49
	v_lshl_add_u32 v40, v25, 4, v26
	v_bitop3_b32 v25, v24, v47, 2 bitop3:0x36
	v_and_b32_e32 v34, 12, v34
	v_bfe_u32 v35, v49, 2, 2
	v_lshlrev_b32_e32 v71, 4, v25
	v_bitop3_b32 v25, v24, v47, 4 bitop3:0x36
	v_bitop3_b32 v34, v34, v45, v35 bitop3:0x36
	v_lshlrev_b32_e32 v16, 4, v16
	v_lshlrev_b32_e32 v73, 4, v25
	v_bitop3_b32 v25, v24, v47, 6 bitop3:0x36
	v_lshl_add_u32 v55, v34, 4, 0
	v_and_b32_e32 v34, 0xffffff00, v16
	v_and_b32_e32 v57, 0xf0, v16
	v_lshlrev_b32_e32 v16, 2, v44
	v_lshlrev_b32_e32 v75, 4, v25
	v_bitop3_b32 v25, v24, v47, 8 bitop3:0x36
	v_add_u32_e32 v56, 0, v34
	v_and_b32_e32 v16, 12, v16
	v_bfe_u32 v34, v44, 2, 2
	v_lshlrev_b32_e32 v21, 3, v17
	v_lshlrev_b32_e32 v77, 4, v25
	v_bitop3_b32 v25, v24, v47, 10 bitop3:0x36
	v_bitop3_b32 v16, v16, v45, v34 bitop3:0x36
	v_add_u32_e32 v50, s74, v20
	v_lshlrev_b32_e32 v79, 4, v25
	v_bitop3_b32 v25, v24, v47, 12 bitop3:0x36
	v_bitop3_b32 v24, v24, v47, 14 bitop3:0x36
	v_lshl_add_u32 v59, v16, 4, 0
	v_or_b32_e32 v16, 7, v21
	v_lshl_add_u32 v23, v17, 11, 0
	v_lshl_add_u32 v51, v17, 9, v50
	v_lshlrev_b32_e32 v83, 4, v24
	v_lshlrev_b32_e32 v24, 4, v17
	v_cmp_gt_i32_e64 s[42:43], 0, v17
	v_cmp_gt_i32_e64 s[44:45], 1, v17
	v_cmp_gt_i32_e64 s[46:47], 2, v17
	v_cmp_gt_i32_e64 s[48:49], 3, v17
	v_cmp_gt_i32_e64 s[50:51], 4, v17
	v_cmp_gt_i32_e64 s[52:53], 5, v17
	v_cmp_gt_i32_e64 s[54:55], 6, v17
	v_cmp_gt_i32_e64 s[56:57], 7, v17
	v_lshlrev_b32_e32 v17, 8, v16
	v_bfe_u32 v16, v16, 2, 2
	v_bitop3_b32 v16, v16, v29, 12 bitop3:0x36
	v_lshlrev_b32_e32 v16, 4, v16
	v_add3_u32 v60, 0, v16, v17
	v_or_b32_e32 v16, 6, v21
	v_lshlrev_b32_e32 v17, 8, v16
	v_bfe_u32 v16, v16, 2, 2
	v_bitop3_b32 v16, v16, v29, 8 bitop3:0x36
	v_lshlrev_b32_e32 v16, 4, v16
	v_add3_u32 v61, 0, v16, v17
	v_or_b32_e32 v16, 5, v21
	v_lshlrev_b32_e32 v17, 8, v16
	v_bfe_u32 v16, v16, 2, 2
	v_bitop3_b32 v16, v16, v29, 4 bitop3:0x36
	v_lshlrev_b32_e32 v16, 4, v16
	v_add3_u32 v62, 0, v16, v17
	v_or_b32_e32 v16, 4, v21
	v_lshlrev_b32_e32 v17, 8, v16
	v_lshrrev_b32_e32 v16, 2, v16
	v_bitop3_b32 v16, v16, v29, 3 bitop3:0x6c
	v_lshlrev_b32_e32 v16, 4, v16
	v_add3_u32 v63, 0, v16, v17
	v_and_b32_e32 v16, 2, v31
	v_bitop3_b32 v17, v16, v29, 12 bitop3:0x36
	v_lshl_add_u32 v64, v17, 4, v23
	v_bitop3_b32 v17, v16, v29, 8 bitop3:0x36
	v_bitop3_b32 v16, v16, v29, 4 bitop3:0x36
	v_lshlrev_b32_e32 v81, 4, v25
	v_ashrrev_i32_e32 v25, 31, v24
	v_lshl_add_u32 v66, v16, 4, v23
	v_bitop3_b32 v16, v31, v29, 2 bitop3:0x6c
	s_add_i32 s0, s94, 4
	v_lshl_add_u32 v65, v17, 4, v23
	v_lshl_add_u32 v29, v16, 4, v23
	v_lshl_add_u64 v[16:17], v[24:25], 1, s[4:5]
	s_cmp_gt_u32 s0, 10
	v_lshl_add_u64 v[16:17], v[16:17], 0, v[136:137]
	s_mov_b64 s[0:1], 0x2ac00000
	v_lshl_add_u64 v[34:35], v[16:17], 0, s[0:1]
	v_readlane_b32 s0, v248, 57
	s_cselect_b64 s[12:13], -1, 0
	v_lshlrev_b32_e32 v28, 7, v19
	s_add_u32 s0, s0, s36
	v_readlane_b32 s1, v248, 58
	v_lshlrev_b32_e32 v27, 2, v19
	v_add_u32_e32 v42, v26, v38
	v_lshlrev_b32_e32 v84, 4, v22
	v_and_b32_e32 v22, 0x780, v28
	v_or_b32_e32 v26, 0x1800, v28
	v_or_b32_e32 v28, 0x3800, v28
	v_lshlrev_b32_e32 v54, 8, v49
	v_lshlrev_b32_e32 v58, 8, v44
	v_mov_b32_e32 v21, v137
	s_addc_u32 s1, s1, s37
	v_cmp_lt_u32_e64 s[40:41], 63, v150
	v_lshl_add_u32 v52, v19, 1, s89
	v_lshl_add_u64 v[36:37], s[0:1], 0, v[20:21]
	s_mov_b64 s[14:15], 0
	v_add_u32_e32 v53, v53, v32
	v_add_u32_e32 v54, v55, v54
	v_add_u32_e32 v55, v56, v57
	v_add_u32_e32 v56, v59, v58
	v_lshlrev_b32_e32 v57, 1, v18
	v_add_u32_e32 v58, v23, v27
	v_add_u32_e32 v59, v60, v30
	v_add_u32_e32 v60, v61, v30
	v_add_u32_e32 v61, v62, v30
	v_add_u32_e32 v62, v63, v30
	v_add_u32_e32 v63, v64, v30
	v_add_u32_e32 v64, v65, v30
	v_add_u32_e32 v65, v66, v30
	v_add_u32_e32 v66, v29, v30
	v_add_u32_e32 v67, v39, v38
	v_add_u32_e32 v68, v40, v38
	v_add_u32_e32 v69, v41, v43
	v_add_u32_e32 v70, v42, v70
	v_add_u32_e32 v71, v41, v71
	v_add_u32_e32 v72, v42, v72
	v_add_u32_e32 v73, v41, v73
	v_add_u32_e32 v74, v42, v74
	v_add_u32_e32 v75, v41, v75
	v_add_u32_e32 v76, v42, v76
	v_add_u32_e32 v77, v41, v77
	v_add_u32_e32 v78, v42, v78
	v_add_u32_e32 v79, v41, v79
	v_add_u32_e32 v80, v42, v80
	v_add_u32_e32 v81, v41, v81
	v_add_u32_e32 v82, v42, v82
	v_add_u32_e32 v83, v41, v83
	v_add_u32_e32 v84, v42, v84
	v_lshlrev_b32_e32 v136, 1, v22
	v_lshlrev_b32_e32 v38, 1, v26
	v_lshlrev_b32_e32 v40, 1, v28
	v_readlane_b32 s18, v248, 59
	v_readlane_b32 s19, v248, 60
	s_waitcnt vmcnt(0)
	s_branch .LBB0_204

; __device__ __forceinline__ void swz_put(LAS unsigned char* reg, int i, u32x4 v) { *(LAS u32x4*)(reg + off_b((unsigned)(i >> 4), (unsigned)(i & 15))) = v; }
; __device__ __forceinline__ void a1_phase(const Params& P, int layer, LAS unsigned char* lds, int tid) {
;     ...
;     for (; it < 3072; it += G) {
;         const int cidx = it / 6, h = it % 6;
;         const float lb0 = lb_of(P, layer, h * 128 + 2 * kp), lb1 = lb_of(P, layer, h * 128 + 2 * kp + 1), om0 = 1.f - lb0, om1 = 1.f - lb1;
; #pragma unroll
;         for (int u = 0; u < 2; ++u) { raw_put(lds + R_Q, tid + 512 * u, R.z[u]); swz_put(lds + R_V, tid + 512 * u, R.v[u]); }
;         __syncthreads();
;         if (it + G < 3072) a1_load(R, P, it + G, tid);
.LBB0_208:
	s_add_i32 s28, s18, s26
	s_cmpk_gt_i32 s28, 0xbff
	s_cselect_b64 s[0:1], -1, 0
	s_and_b64 vcc, exec, s[0:1]
	s_waitcnt vmcnt(8)
	ds_write_b128 v53, v[0:3] offset:16384
	ds_write_b128 v54, v[4:7] offset:49152
	ds_write_b128 v55, v[8:11] offset:16384
	ds_write_b128 v56, v[12:15] offset:49152
	s_waitcnt lgkmcnt(0)
	s_barrier
	s_cbranch_vccnz .LBB0_210
	s_mul_hi_i32 s19, s28, 0x2aaaaaab
	s_lshr_b32 s39, s19, 31
	s_add_i32 s19, s19, s39
	s_mul_i32 s39, s19, -6
	s_add_i32 s58, s28, s39
	s_ashr_i32 s59, s58, 31
	s_lshl_b32 s19, s19, 6
	s_lshl_b64 s[58:59], s[58:59], 23
	s_add_u32 s60, s8, s58
	v_add_u32_e32 v0, s19, v49
	v_add_u32_e32 v8, s19, v44
	s_addc_u32 s61, s9, s59
	v_ashrrev_i32_e32 v1, 31, v0
	v_ashrrev_i32_e32 v9, 31, v8
	s_add_u32 s58, s10, s58
	v_lshlrev_b64 v[0:1], 8, v[0:1]
	v_lshlrev_b64 v[8:9], 8, v[8:9]
	s_addc_u32 s59, s11, s59
	v_or_b32_e32 v0, v0, v57
	v_or_b32_e32 v8, v8, v57
	v_lshl_add_u64 v[2:3], s[60:61], 0, v[0:1]
	v_lshl_add_u64 v[4:5], s[58:59], 0, v[0:1]
	v_lshl_add_u64 v[10:11], s[60:61], 0, v[8:9]
	v_lshl_add_u64 v[12:13], s[58:59], 0, v[8:9]
	global_load_dwordx4 v[0:3], v[2:3], off
	s_nop 0
	global_load_dwordx4 v[4:7], v[4:5], off
	s_nop 0
	global_load_dwordx4 v[8:11], v[10:11], off
	s_nop 0
	global_load_dwordx4 v[12:15], v[12:13], off
